# prologue cg grid.sync replaced by an inlined XCD-hierarchical grid barrier (copy of the in-loop barrier)
# speedup vs baseline: 1.0124x; 1.0124x over previous
.LBB0_84:
	v_readlane_b32 s14, v254, 0
	v_readlane_b32 s15, v254, 1
	s_add_u32 s4, s14, 0x8578000
	s_addc_u32 s5, s15, 0
	s_add_u32 s68, s14, 0xcd78000
	s_addc_u32 s69, s15, 0
	s_add_u32 s70, s14, 0x11578000
	s_addc_u32 s71, s15, 0
	s_add_u32 s72, s14, 0x23578000
	s_addc_u32 s73, s15, 0
	s_lshl_b32 s96, s60, 3
	s_add_u32 s6, s14, 0x2d778200
	s_addc_u32 s7, s15, 0
	s_add_u32 s8, s14, 0x2d778400
	s_addc_u32 s9, s15, 0
	s_add_u32 s10, s14, 0x2d778500
	s_addc_u32 s11, s15, 0
	s_add_u32 s12, s14, 0x2d778600
	s_addc_u32 s13, s15, 0
	v_writelane_b32 v254, s12, 4
	s_mul_i32 s61, s61, s60
	s_mov_b32 s25, 0
	v_writelane_b32 v254, s13, 5
	s_add_u32 s12, s14, 0x2d778700
	s_addc_u32 s13, s15, 0
	v_writelane_b32 v254, s12, 6
	v_mov_b32_e32 v17, 0
	v_mov_b32_e32 v209, 0x358637bd
	v_writelane_b32 v254, s13, 7
	s_add_u32 s12, s14, 0x2d778800
	s_addc_u32 s13, s15, 0
	v_writelane_b32 v254, s12, 8
	v_mov_b32_e32 v210, 1
	v_mov_b32_e32 v213, 0x3e2aaaab
	v_writelane_b32 v254, s13, 9
	s_add_u32 s12, s14, 0x2d778900
	s_addc_u32 s13, s15, 0
	v_writelane_b32 v254, s12, 10
	v_mov_b32_e32 v221, 0x1e364
	v_mov_b32_e32 v222, 0x41b17218
	v_writelane_b32 v254, s13, 11
	s_add_u32 s12, s14, 0x2d778a00
	s_addc_u32 s13, s15, 0
	v_writelane_b32 v254, s12, 12
	s_movk_i32 s54, 0x4000
	s_mov_b32 s55, 0x800000
	v_writelane_b32 v254, s13, 13
	s_add_u32 s12, s14, 0x2d778b00
	s_addc_u32 s13, s15, 0
	v_writelane_b32 v254, s12, 14
	s_movk_i32 s95, 0x47ff
	s_mov_b32 s20, 0x40000
	v_writelane_b32 v254, s13, 15
	s_add_u32 s12, s14, 0x2d778c00
	s_addc_u32 s13, s15, 0
	v_writelane_b32 v254, s12, 16
	s_mov_b32 s21, 0x60000
	s_mov_b32 s66, 0xc0000
	v_writelane_b32 v254, s13, 17
	s_add_u32 s12, s14, 0x2d778d00
	s_addc_u32 s13, s15, 0
	v_writelane_b32 v254, s12, 18
	s_mov_b32 s67, 0x10000
	s_mov_b32 s74, 0x30000
	v_writelane_b32 v254, s13, 19
	s_add_u32 s12, s14, 0x2d778e00
	s_addc_u32 s13, s15, 0
	v_writelane_b32 v254, s12, 20
	s_mov_b32 s75, 0x50000
	s_mov_b32 s30, 0x70000
	v_writelane_b32 v254, s13, 21
	s_add_u32 s12, s14, 0x2d778f00
	s_addc_u32 s13, s15, 0
	v_writelane_b32 v254, s12, 22
	s_mov_b32 s31, 0x90000
	s_movk_i32 s76, 0x2c00
	v_writelane_b32 v254, s13, 23
	s_add_u32 s12, s14, 0x2d779000
	s_addc_u32 s13, s15, 0
	v_writelane_b32 v254, s12, 24
	s_movk_i32 s77, 0x1000
	s_mov_b32 s78, 0x8000
	v_writelane_b32 v254, s13, 25
	s_add_u32 s12, s14, 0x2d779100
	s_addc_u32 s13, s15, 0
	v_writelane_b32 v254, s12, 26
	s_mov_b32 s79, 0x18000
	s_movk_i32 s80, 0x110
	v_writelane_b32 v254, s13, 27
	s_add_u32 s12, s14, 0x2d779200
	s_addc_u32 s13, s15, 0
	v_writelane_b32 v254, s12, 28
	s_mov_b32 s81, 0xbe000000
	s_mov_b32 s82, 0x28000
	v_writelane_b32 v254, s13, 29
	s_add_u32 s12, s14, 0x2d779300
	s_addc_u32 s13, s15, 0
	s_cmp_eq_u32 s3, 15
	s_cselect_b64 s[16:17], -1, 0
	v_writelane_b32 v254, s16, 30
	s_cmp_eq_u32 s3, 14
	s_mov_b64 s[18:19], -1
	v_writelane_b32 v254, s17, 31
	s_cselect_b64 s[16:17], -1, 0
	v_writelane_b32 v254, s16, 32
	s_cmp_eq_u32 s3, 13
	s_mov_b64 s[92:93], 0x2000
	v_writelane_b32 v254, s17, 33
	s_cselect_b64 s[16:17], -1, 0
	v_writelane_b32 v254, s16, 34
	s_cmp_eq_u32 s3, 12
	s_mov_b64 s[34:35], 0x80
	v_writelane_b32 v254, s17, 35
	s_cselect_b64 s[16:17], -1, 0
	v_writelane_b32 v254, s16, 36
	s_cmp_eq_u32 s3, 11
	s_mov_b32 s24, s25
	v_writelane_b32 v254, s17, 37
	s_cselect_b64 s[16:17], -1, 0
	v_writelane_b32 v254, s16, 38
	s_cmp_eq_u32 s3, 10
	s_nop 0
	v_writelane_b32 v254, s17, 39
	s_cselect_b64 s[16:17], -1, 0
	v_writelane_b32 v254, s16, 40
	s_cmp_eq_u32 s3, 9
	s_nop 0
	v_writelane_b32 v254, s17, 41
	s_cselect_b64 s[16:17], -1, 0
	v_writelane_b32 v254, s16, 42
	s_cmp_eq_u32 s3, 8
	s_nop 0
	v_writelane_b32 v254, s17, 43
	s_cselect_b64 s[16:17], -1, 0
	v_writelane_b32 v254, s16, 44
	s_cmp_eq_u32 s3, 7
	s_nop 0
	v_writelane_b32 v254, s17, 45
	s_cselect_b64 s[16:17], -1, 0
	v_writelane_b32 v254, s16, 46
	s_cmp_eq_u32 s3, 6
	s_nop 0
	v_writelane_b32 v254, s17, 47
	s_cselect_b64 s[16:17], -1, 0
	v_writelane_b32 v254, s16, 48
	s_cmp_eq_u32 s3, 5
	s_nop 0
	v_writelane_b32 v254, s17, 49
	s_cselect_b64 s[16:17], -1, 0
	v_writelane_b32 v254, s16, 50
	s_cmp_eq_u32 s3, 4
	s_nop 0
	v_writelane_b32 v254, s17, 51
	s_cselect_b64 s[16:17], -1, 0
	v_writelane_b32 v254, s16, 52
	s_cmp_eq_u32 s3, 3
	s_nop 0
	v_writelane_b32 v254, s17, 53
	s_cselect_b64 s[16:17], -1, 0
	v_writelane_b32 v254, s16, 54
	s_cmp_eq_u32 s3, 2
	s_nop 0
	v_writelane_b32 v254, s17, 55
	s_cselect_b64 s[16:17], -1, 0
	v_writelane_b32 v254, s16, 56
	s_cmp_eq_u32 s3, 1
	s_nop 0
	v_writelane_b32 v254, s17, 57
	s_cselect_b64 s[16:17], -1, 0
	v_writelane_b32 v254, s16, 58
	s_cmp_eq_u32 s3, 0
	s_nop 0
	v_writelane_b32 v254, s17, 59
	s_cselect_b64 s[16:17], -1, 0
	s_lshl_b32 s3, s3, 8
	s_add_u32 s0, s0, s3
	v_writelane_b32 v254, s16, 60
	s_addc_u32 s1, s1, 0
	s_nop 0
	v_writelane_b32 v254, s17, 61
	s_add_u32 s16, s0, 0x1400
	s_addc_u32 s17, s1, 0
	s_add_u32 s0, s0, 0x2400
	s_addc_u32 s1, s1, 0
	v_writelane_b32 v255, s0, 0
	v_writelane_b32 v254, s16, 62
	s_nop 0
	v_writelane_b32 v255, s1, 1
	s_add_u32 s0, s14, 0x2d77b400
	s_addc_u32 s1, s15, 0
	v_writelane_b32 v255, s0, 2
	v_writelane_b32 v254, s17, 63
	s_mov_b32 s16, 0xc000
	v_writelane_b32 v255, s1, 3
	s_add_u32 s0, s14, 0x2d77b500
	s_addc_u32 s1, s15, 0
	v_writelane_b32 v255, s0, 4
	s_mov_b32 s17, 0x20000
	s_nop 0
	v_writelane_b32 v255, s1, 5
	s_add_u32 s0, s14, 0x378000
	v_writelane_b32 v255, s0, 6
	s_addc_u32 s0, s15, 0
	v_writelane_b32 v255, s0, 7
	s_ashr_i32 s0, s60, 3
	s_max_i32 s3, s0, 1
	v_writelane_b32 v255, s64, 8
	s_load_dword s0, s[64:65], 0x100
	v_cvt_f32_u32_e32 v0, s3
	s_ashr_i32 s33, s60, 31
	v_writelane_b32 v255, s65, 9
	s_barrier
	s_waitcnt lgkmcnt(0)
	s_mul_i32 s61, s61, s0
	s_add_u32 s0, s14, 0x3378000
	v_rcp_iflag_f32_e32 v0, v0
	v_writelane_b32 v255, s0, 10
	s_addc_u32 s0, s15, 0
	v_writelane_b32 v255, s0, 11
	s_add_u32 s0, s14, 0x1378000
	v_writelane_b32 v255, s0, 12
	s_addc_u32 s0, s15, 0
	v_writelane_b32 v255, s0, 13
	s_add_u32 s0, s14, 0x3b78000
	v_mul_f32_e32 v0, 0x4f7ffffe, v0
	v_writelane_b32 v255, s0, 14
	s_addc_u32 s0, s15, 0
	v_cvt_u32_f32_e32 v0, v0
	v_writelane_b32 v255, s0, 15
	s_add_u32 s0, s14, 0x4378000
	v_writelane_b32 v255, s0, 16
	s_addc_u32 s0, s15, 0
	v_writelane_b32 v255, s0, 17
	s_add_u32 s0, s14, 0x6f78000
	v_writelane_b32 v255, s0, 18
	s_addc_u32 s0, s15, 0
	v_writelane_b32 v255, s0, 19
	s_sub_i32 s0, 0, s3
	v_readfirstlane_b32 s1, v0
	s_mul_i32 s0, s0, s1
	s_mul_hi_u32 s0, s1, s0
	s_add_i32 s0, s1, s0
	v_writelane_b32 v255, s0, 20
	s_add_u32 s0, s14, 0xcd78c00
	s_addc_u32 s1, s15, 0
	v_writelane_b32 v255, s0, 21
	s_ashr_i32 s97, s96, 31
	v_mbcnt_lo_u32_b32 v0, -1, 0
	v_writelane_b32 v255, s1, 22
	s_add_i32 s0, 0, 0x23ff0
	v_writelane_b32 v255, s0, 23
	s_add_i32 s0, 0, 0x23ff4
	v_writelane_b32 v255, s0, 24
	s_add_i32 s0, 0, 0x1e800
	v_writelane_b32 v255, s0, 25
	s_add_i32 s0, 0, 0x1b000
	v_writelane_b32 v255, s0, 26
	s_add_i32 s0, 0, 0x11880
	v_writelane_b32 v255, s0, 27
	s_add_i32 s0, 0, 0x11890
	v_writelane_b32 v255, s0, 28
	s_add_i32 s0, 0, 0x118a0
	v_writelane_b32 v255, s0, 29
	s_add_i32 s0, 0, 0x118b0
	v_writelane_b32 v255, s0, 30
	s_lshl_b64 s[0:1], s[96:97], 12
	v_writelane_b32 v255, s0, 31
	v_mbcnt_hi_u32_b32 v211, -1, v0
	v_and_b32_e32 v0, 64, v211
	v_writelane_b32 v255, s1, 32
	s_lshl_b64 s[0:1], s[96:97], 13
	v_writelane_b32 v255, s0, 33
	v_add_u32_e32 v212, 64, v0
	s_nop 0
	v_writelane_b32 v255, s1, 34
	v_writelane_b32 v255, s10, 35
	v_xor_b32_e32 v219, 32, v211
	v_xor_b32_e32 v218, 16, v211
	v_writelane_b32 v255, s11, 36
	v_writelane_b32 v255, s62, 37
	v_xor_b32_e32 v220, 4, v211
	v_xor_b32_e32 v215, 2, v211
	v_xor_b32_e32 v214, 1, v211
	s_mov_b32 s64, 0x80000
	s_mov_b32 s65, 0xa0000
	s_mov_b64 s[14:15], 0
	v_writelane_b32 v255, s63, 38

.Lgs0_end:
	s_or_b64 exec, exec, s[0:1]
	s_waitcnt lgkmcnt(0)
	s_barrier
	s_mov_b64 s[18:19], -1
	s_mov_b32 s24, s25
	s_branch .LBB0_87
